# waves 0-3 issue all attention LDS-DMA, no priority changes in the attention loop
# speedup vs baseline: 1.0011x; 1.0011x over previous
.Lattn_dma_a:
	v_cvt_f32_i32_e32 v98, s82
	v_add_u32_e32 v183, s79, v218
	v_add_f32_e32 v98, v155, v98
	v_fma_f32 v224, v200, v98, -v199
	v_fma_f32 v98, 0, v200, v224
	v_add_f32_e32 v99, v200, v224
	v_fma_f32 v100, v200, s64, v224
	v_fma_f32 v101, v200, s65, v224
	v_fma_f32 v102, v200, s66, v224
	v_fma_f32 v103, v200, s67, v224
	v_mul_f32_e32 v240, 0x42000000, v200
	ds_read_b128 v[228:231], v181 offset:53248
	s_waitcnt lgkmcnt(2)
	v_mfma_f32_32x32x16_bf16 v[18:33], v[126:129], v[106:109], v[18:33]
	v_add_f32_e32 v254, v70, v254
	v_add_f32_e32 v255, v252, v255
	v_exp_f32_e32 v71, v71
	v_fma_f32 v104, v200, s68, v224
	v_fma_f32 v105, v200, s69, v224
	ds_read_b128 v[126:129], v181 offset:57344
	v_mfma_f32_32x32x16_bf16 v[2:17], v[118:121], v[106:109], v[2:17]
	v_add_f32_e32 v254, v71, v254
	v_exp_f32_e32 v253, v87
	v_exp_f32_e32 v82, v72
	ds_read_b128 v[118:121], v181 offset:61440
	s_waitcnt lgkmcnt(2)
	v_mfma_f32_32x32x16_bf16 v[50:65], v[122:125], v[110:113], v[50:65]
	v_add_f32_e32 v255, v253, v255
	v_add_f32_e32 v254, v82, v254
	v_exp_f32_e32 v72, v88
	v_fma_f32 v106, v200, s70, v224
	v_fma_f32 v107, v200, s71, v224
	v_add_u32_e32 v179, v179, v226
	ds_read_b128 v[122:125], v179 offset:49152
	v_mfma_f32_32x32x16_bf16 v[34:49], v[228:231], v[110:113], v[34:49]
	v_add_f32_e32 v255, v72, v255
	v_exp_f32_e32 v83, v73
	v_exp_f32_e32 v73, v89
	ds_read_b128 v[228:231], v179 offset:53248
	s_waitcnt lgkmcnt(2)
	v_mfma_f32_32x32x16_bf16 v[18:33], v[126:129], v[110:113], v[18:33]
	v_add_f32_e32 v254, v83, v254
	v_add_f32_e32 v255, v73, v255
	v_exp_f32_e32 v74, v74
	v_fma_f32 v108, v200, s72, v224
	v_fma_f32 v109, v200, s73, v224
	ds_read_b128 v[126:129], v179 offset:57344
	v_mfma_f32_32x32x16_bf16 v[2:17], v[118:121], v[110:113], v[2:17]
	v_add_f32_e32 v254, v74, v254
	v_exp_f32_e32 v90, v90
	v_exp_f32_e32 v75, v75
	ds_read_b128 v[118:121], v179 offset:61440
	s_waitcnt lgkmcnt(2)
	v_mfma_f32_32x32x16_bf16 v[50:65], v[122:125], v[114:117], v[50:65]
	v_add_f32_e32 v255, v90, v255
	v_add_f32_e32 v254, v75, v254
	v_exp_f32_e32 v91, v91
	v_fma_f32 v110, v200, s74, v224
	v_fma_f32 v111, v200, s75, v224
	v_add_u32_e32 v112, v183, v149
	ds_read_b128 v[232:235], v112
	v_mfma_f32_32x32x16_bf16 v[34:49], v[228:231], v[114:117], v[34:49]
	v_add_f32_e32 v255, v91, v255
	v_exp_f32_e32 v76, v76
	v_exp_f32_e32 v92, v92
	ds_read_b128 v[228:231], v112 offset:4096
	s_waitcnt lgkmcnt(2)
	v_mfma_f32_32x32x16_bf16 v[18:33], v[126:129], v[114:117], v[18:33]
	v_add_f32_e32 v254, v76, v254
	v_add_f32_e32 v255, v92, v255
	v_exp_f32_e32 v77, v77
	v_fma_f32 v112, v200, s76, v224
	v_fma_f32 v113, v200, s77, v224
	v_add_u32_e32 v179, v183, v208
	ds_read_b128 v[236:239], v179
	v_mfma_f32_32x32x16_bf16 v[2:17], v[118:121], v[114:117], v[2:17]
	v_add_f32_e64 v114, v240, v98
	v_add_f32_e64 v115, v240, v99
	v_add_f32_e64 v128, v240, v112
	v_add_f32_e64 v129, v240, v113
	v_add_f32_e64 v126, v240, v110
	v_add_f32_e64 v127, v240, v111
	v_add_f32_e32 v124, v240, v108
	v_add_f32_e32 v125, v240, v109
	v_add_f32_e32 v122, v240, v106
	v_add_f32_e32 v123, v240, v107
	v_add_f32_e32 v120, v240, v104
	v_add_f32_e32 v121, v240, v105
	v_add_f32_e32 v118, v240, v102
	v_add_f32_e32 v119, v240, v103
	v_add_f32_e32 v116, v240, v100
	v_add_f32_e32 v117, v240, v101
	ds_read_b128 v[240:243], v179 offset:4096
	s_waitcnt lgkmcnt(2)
	v_mfma_f32_32x32x16_bf16 v[98:113], v[232:235], v[130:133], v[98:113]
	v_add_f32_e32 v254, v77, v254
	v_exp_f32_e32 v93, v93
	v_exp_f32_e32 v78, v78
	v_add_u32_e32 v179, v183, v209
	ds_read_b128 v[232:235], v179
	v_mfma_f32_32x32x16_bf16 v[114:129], v[228:231], v[130:133], v[114:129]
	v_add_f32_e32 v255, v93, v255
	v_add_f32_e32 v254, v78, v254
	v_exp_f32_e32 v94, v94
	v_exp_f32_e32 v79, v79
	ds_read_b128 v[228:231], v179 offset:4096
	s_waitcnt lgkmcnt(2)
	v_mfma_f32_32x32x16_bf16 v[98:113], v[236:239], v[134:137], v[98:113]
	v_add_f32_e32 v255, v94, v255
	v_add_f32_e32 v254, v79, v254
	v_exp_f32_e32 v95, v95
	v_exp_f32_e32 v80, v80
	v_add_u32_e32 v179, v183, v226
	ds_read_b128 v[236:239], v179
	v_mfma_f32_32x32x16_bf16 v[114:129], v[240:243], v[134:137], v[114:129]
	v_add_f32_e32 v255, v95, v255
	v_add_f32_e32 v254, v80, v254
	v_exp_f32_e32 v96, v96
	v_exp_f32_e32 v81, v81
	ds_read_b128 v[240:243], v179 offset:4096
	s_waitcnt lgkmcnt(2)
	v_mfma_f32_32x32x16_bf16 v[98:113], v[232:235], v[138:141], v[98:113]
	v_add_f32_e32 v255, v96, v255
	v_add_f32_e32 v254, v81, v254
	v_exp_f32_e32 v97, v97
	v_mfma_f32_32x32x16_bf16 v[114:129], v[228:231], v[138:141], v[114:129]
	v_add_f32_e32 v255, v97, v255
	v_add_f32_e32 v254, v255, v254
	s_waitcnt lgkmcnt(0)
	v_mfma_f32_32x32x16_bf16 v[98:113], v[236:239], v[142:145], v[98:113]
	v_mfma_f32_32x32x16_bf16 v[114:129], v[240:243], v[142:145], v[114:129]
	s_cmp_lg_u32 s4, 0
	s_cbranch_scc0 .LBB0_471
	s_waitcnt vmcnt(8) lgkmcnt(0)
	s_barrier
	s_andn2_b32 s4, s99, s2
	s_cbranch_scc0 .LBB0_460
	v_add_f32_e32 v179, v198, v254
	s_branch .LBB0_464

.Lattn_dma_b:
	v_cvt_f32_i32_e32 v66, s78
	v_exp_f32_e32 v231, v98
	v_add_f32_e32 v66, v155, v66
	v_fma_f32 v230, v228, v66, -v199
	v_add_u32_e32 v229, s10, v218
	v_exp_f32_e32 v233, v114
	v_fma_f32 v66, 0, v228, v230
	v_exp_f32_e32 v234, v99
	v_exp_f32_e32 v235, v115
	v_add_f32_e32 v67, v228, v230
	v_exp_f32_e32 v236, v100
	v_exp_f32_e32 v237, v116
	v_exp_f32_e32 v238, v101
	v_exp_f32_e32 v239, v117
	v_fma_f32 v68, v228, s64, v230
	v_fma_f32 v69, v228, s65, v230
	v_fma_f32 v70, v228, s66, v230
	v_fma_f32 v71, v228, s67, v230
	v_cvt_pk_bf16_f32 v98, v249, v250
	v_cvt_pk_bf16_f32 v99, v195, v251
	v_cvt_pk_bf16_f32 v100, v252, v253
	v_cvt_pk_bf16_f32 v101, v72, v73
	v_cvt_pk_bf16_f32 v114, v90, v91
	v_cvt_pk_bf16_f32 v115, v92, v93
	v_cvt_pk_bf16_f32 v116, v94, v95
	v_cvt_pk_bf16_f32 v117, v96, v97
	v_mul_f32_e32 v232, 0x42000000, v228
	v_exp_f32_e32 v240, v102
	v_exp_f32_e32 v241, v118
	v_exp_f32_e32 v242, v103
	v_exp_f32_e32 v243, v119
	ds_read_b128 v[90:93], v227 offset:53248
	s_waitcnt lgkmcnt(2)
	v_mfma_f32_32x32x16_bf16 v[18:33], v[86:89], v[74:77], v[18:33]
	v_add_f32_e32 v254, 0, v231
	v_add_f32_e32 v255, 0, v233
	v_fma_f32 v72, v228, s68, v230
	v_fma_f32 v73, v228, s69, v230
	v_exp_f32_e32 v181, v104
	v_exp_f32_e32 v183, v120
	ds_read_b128 v[86:89], v227 offset:57344
	v_mfma_f32_32x32x16_bf16 v[2:17], v[82:85], v[74:77], v[2:17]
	v_add_f32_e32 v254, v234, v254
	v_add_f32_e32 v255, v235, v255
	v_exp_f32_e32 v195, v105
	v_exp_f32_e32 v200, v121
	ds_read_b128 v[82:85], v227 offset:61440
	s_waitcnt lgkmcnt(2)
	v_mfma_f32_32x32x16_bf16 v[50:65], v[78:81], v[98:101], v[50:65]
	v_add_f32_e32 v254, v236, v254
	v_add_f32_e32 v255, v237, v255
	v_fma_f32 v74, v228, s70, v230
	v_fma_f32 v75, v228, s71, v230
	v_exp_f32_e32 v224, v106
	v_exp_f32_e32 v122, v122
	v_add_u32_e32 v78, v198, v226
	ds_read_b128 v[94:97], v78 offset:49152
	v_mfma_f32_32x32x16_bf16 v[34:49], v[90:93], v[98:101], v[34:49]
	v_add_f32_e32 v254, v238, v254
	v_add_f32_e32 v255, v239, v255
	v_exp_f32_e32 v225, v107
	v_exp_f32_e32 v123, v123
	ds_read_b128 v[90:93], v78 offset:53248
	s_waitcnt lgkmcnt(2)
	v_mfma_f32_32x32x16_bf16 v[18:33], v[86:89], v[98:101], v[18:33]
	v_add_f32_e32 v254, v240, v254
	v_add_f32_e32 v255, v241, v255
	v_fma_f32 v76, v228, s72, v230
	v_fma_f32 v77, v228, s73, v230
	v_exp_f32_e32 v227, v108
	v_exp_f32_e32 v124, v124
	ds_read_b128 v[86:89], v78 offset:57344
	v_mfma_f32_32x32x16_bf16 v[2:17], v[82:85], v[98:101], v[2:17]
	v_add_f32_e32 v254, v242, v254
	v_add_f32_e32 v255, v243, v255
	v_exp_f32_e32 v244, v109
	v_exp_f32_e32 v125, v125
	ds_read_b128 v[98:101], v78 offset:61440
	s_waitcnt lgkmcnt(2)
	v_mfma_f32_32x32x16_bf16 v[50:65], v[94:97], v[114:117], v[50:65]
	v_add_f32_e32 v254, v181, v254
	v_add_f32_e32 v255, v183, v255
	v_fma_f32 v78, v228, s74, v230
	v_fma_f32 v79, v228, s75, v230
	v_exp_f32_e32 v245, v110
	v_exp_f32_e32 v126, v126
	v_add_u32_e32 v80, v229, v149
	ds_read_b128 v[102:105], v80
	v_mfma_f32_32x32x16_bf16 v[34:49], v[90:93], v[114:117], v[34:49]
	v_add_f32_e32 v254, v195, v254
	v_add_f32_e32 v255, v200, v255
	v_exp_f32_e32 v246, v111
	v_exp_f32_e32 v127, v127
	ds_read_b128 v[106:109], v80 offset:4096
	s_waitcnt lgkmcnt(2)
	v_mfma_f32_32x32x16_bf16 v[18:33], v[86:89], v[114:117], v[18:33]
	v_add_f32_e32 v254, v224, v254
	v_add_f32_e32 v255, v122, v255
	v_fma_f32 v80, v228, s76, v230
	v_fma_f32 v81, v228, s77, v230
	v_exp_f32_e32 v247, v112
	v_exp_f32_e32 v128, v128
	v_add_u32_e32 v110, v229, v208
	ds_read_b128 v[118:121], v110
	v_mfma_f32_32x32x16_bf16 v[2:17], v[98:101], v[114:117], v[2:17]
	v_add_f32_e32 v254, v225, v254
	v_add_f32_e32 v255, v123, v255
	v_add_f32_e64 v82, v232, v66
	v_add_f32_e64 v83, v232, v67
	v_add_f32_e64 v96, v232, v80
	v_add_f32_e64 v97, v232, v81
	v_add_f32_e64 v94, v232, v78
	v_add_f32_e64 v95, v232, v79
	v_add_f32_e32 v92, v232, v76
	v_add_f32_e32 v93, v232, v77
	v_add_f32_e32 v90, v232, v74
	v_add_f32_e32 v91, v232, v75
	v_add_f32_e32 v88, v232, v72
	v_add_f32_e32 v89, v232, v73
	v_add_f32_e32 v86, v232, v70
	v_add_f32_e32 v87, v232, v71
	v_add_f32_e32 v84, v232, v68
	v_add_f32_e32 v85, v232, v69
	v_exp_f32_e32 v228, v113
	v_exp_f32_e32 v129, v129
	ds_read_b128 v[98:101], v110 offset:4096
	s_waitcnt lgkmcnt(2)
	v_mfma_f32_32x32x16_bf16 v[66:81], v[102:105], v[130:133], v[66:81]
	v_add_f32_e32 v254, v227, v254
	v_add_f32_e32 v255, v124, v255
	v_add_f32_e32 v254, v244, v254
	v_add_u32_e32 v110, v229, v209
	ds_read_b128 v[102:105], v110
	v_mfma_f32_32x32x16_bf16 v[82:97], v[106:109], v[130:133], v[82:97]
	v_add_f32_e32 v255, v125, v255
	v_add_f32_e32 v254, v245, v254
	v_add_f32_e32 v255, v126, v255
	ds_read_b128 v[106:109], v110 offset:4096
	s_waitcnt lgkmcnt(2)
	v_mfma_f32_32x32x16_bf16 v[66:81], v[118:121], v[134:137], v[66:81]
	v_add_f32_e32 v254, v246, v254
	v_add_f32_e32 v255, v127, v255
	v_add_f32_e32 v254, v247, v254
	v_add_u32_e32 v114, v229, v226
	ds_read_b128 v[110:113], v114
	v_mfma_f32_32x32x16_bf16 v[82:97], v[98:101], v[134:137], v[82:97]
	v_add_f32_e32 v255, v128, v255
	v_add_f32_e32 v254, v228, v254
	v_add_f32_e32 v255, v129, v255
	v_add_f32_e32 v254, v255, v254
	ds_read_b128 v[98:101], v114 offset:4096
	s_waitcnt lgkmcnt(2)
	v_mfma_f32_32x32x16_bf16 v[66:81], v[102:105], v[138:141], v[66:81]
	v_cvt_pk_bf16_f32 v114, v122, v123
	v_cvt_pk_bf16_f32 v115, v124, v125
	v_cvt_pk_bf16_f32 v116, v126, v127
	v_cvt_pk_bf16_f32 v117, v128, v129
	v_mfma_f32_32x32x16_bf16 v[82:97], v[106:109], v[138:141], v[82:97]
	v_cvt_pk_bf16_f32 v106, v224, v225
	v_cvt_pk_bf16_f32 v107, v227, v244
	v_cvt_pk_bf16_f32 v108, v245, v246
	v_cvt_pk_bf16_f32 v109, v247, v228
	s_waitcnt lgkmcnt(0)
	v_mfma_f32_32x32x16_bf16 v[66:81], v[110:113], v[142:145], v[66:81]
	v_cvt_pk_bf16_f32 v110, v233, v235
	v_cvt_pk_bf16_f32 v111, v237, v239
	v_cvt_pk_bf16_f32 v112, v241, v243
	v_cvt_pk_bf16_f32 v113, v183, v200
	v_mfma_f32_32x32x16_bf16 v[82:97], v[98:101], v[142:145], v[82:97]
	s_add_i32 s10, s4, 1
	s_cmp_lg_u32 s4, 2
	s_cselect_b32 s62, s10, 0
	s_add_i32 s4, s5, 1
	s_cmp_lg_u32 s5, 2
	s_cselect_b32 s10, s4, 0
	s_add_i32 s34, s34, 2
	v_add_f32_e32 v198, v179, v254
	v_cvt_pk_bf16_f32 v98, v231, v234
	v_cvt_pk_bf16_f32 v99, v236, v238
	v_cvt_pk_bf16_f32 v100, v240, v242
	v_cvt_pk_bf16_f32 v101, v181, v195
	s_cmp_ge_i32 s61, s48
	s_cbranch_scc1 .LBB0_473
	s_mov_b32 s60, s63
	s_add_i32 s61, s34, -2
	s_cmp_gt_i32 s61, s48
	s_cbranch_scc1 .LBB0_469
.LBB0_468:
	s_waitcnt vmcnt(8) lgkmcnt(0)
	s_barrier
	s_cmp_lg_u32 s99, 0
	s_cbranch_scc1 .Lattn_A_fast
	s_branch .LBB0_452
.LBB0_469:
	s_waitcnt vmcnt(4) lgkmcnt(0)
	s_barrier
	s_andn2_b64 vcc, exec, s[2:3]
	s_cbranch_vccz .LBB0_453
	s_branch .LBB0_454
.LBB0_471:
	s_mov_b64 s[4:5], -1
	s_waitcnt vmcnt(4) lgkmcnt(0)
	s_barrier
	s_andn2_b64 vcc, exec, s[2:3]
	s_cbranch_vccz .LBB0_461
	s_branch .LBB0_462
